# attention loops accumulate O in place (no per-tile 64-register copies), on top of pipelined partial sums
# speedup vs baseline: 1.0068x; 1.0068x over previous
; template <int TYPE>
; __device__ __forceinline__ void attn_item(const Params& p, int layer, int head, int qb, int mode, LAS unsigned char* lds) {
;     ...
;             { auto rr = __builtin_amdgcn_permlane32_swap(__float_as_uint(ps), __float_as_uint(ps), false, false);
;               ps = __uint_as_float(rr[0]) + __uint_as_float(rr[1]); }
;             l_reg = l_reg * alpha + ps;
.LBB0_817:
	v_add_f32_e32 v66, v237, v238
	v_fmac_f32_e32 v66, v199, v236
	v_mov_b32_e32 v199, v66

; template <int VB>
; __device__ __forceinline__ void pv_tile(f32x16* o, int vb0, bf16x8 pa0, bf16x8 pa1, bf16x8 pa2, bf16x8 pa3) {
;     ...
;     PV_D0(0); PV_D0(1); PV_D0(2); PV_D0(3);
;     ...
; }
; template <int TYPE>
; __device__ __forceinline__ void attn_item(const Params& p, int layer, int head, int qb, int mode, LAS unsigned char* lds) {
;     ...
;             if (bf == 0) pv_tile<0>(o, vb0, pa0, pa1, pa2, pa3); else pv_tile<1>(o, vb0, pa0, pa1, pa2, pa3);
.LBB0_826:
	s_cmp_lg_u32 s28, 0
	s_mov_b64 s[40:41], -1
	s_cbranch_scc0 .LBB0_828
	ds_read_b64_tr_b16 v[82:83], v234 offset:0x4000
	ds_read_b64_tr_b16 v[84:85], v234 offset:0x4800
	ds_read_b64_tr_b16 v[86:87], v234 offset:0x5000
	ds_read_b64_tr_b16 v[88:89], v234 offset:0x5800
	ds_read_b64_tr_b16 v[90:91], v234 offset:0x6000
	ds_read_b64_tr_b16 v[92:93], v234 offset:0x6800
	ds_read_b64_tr_b16 v[94:95], v234 offset:0x7000
	ds_read_b64_tr_b16 v[96:97], v234 offset:0x7800
	s_waitcnt lgkmcnt(0)
	s_nop 0
	v_mfma_f32_32x32x16_bf16 v[2:17], v[178:181], v[82:85], v[2:17]
	ds_read_b64_tr_b16 v[98:99], v234 offset:0x4200
	ds_read_b64_tr_b16 v[100:101], v234 offset:0x4a00
	ds_read_b64_tr_b16 v[102:103], v234 offset:0x5200
	ds_read_b64_tr_b16 v[104:105], v234 offset:0x5a00
	ds_read_b64_tr_b16 v[106:107], v234 offset:0x6200
	ds_read_b64_tr_b16 v[108:109], v234 offset:0x6a00
	ds_read_b64_tr_b16 v[110:111], v234 offset:0x7200
	v_mfma_f32_32x32x16_bf16 v[2:17], v[182:185], v[86:89], v[2:17]
	ds_read_b64_tr_b16 v[112:113], v234 offset:0x7a00
	s_waitcnt lgkmcnt(0)
	v_mfma_f32_32x32x16_bf16 v[2:17], v[186:189], v[90:93], v[2:17]
	v_mfma_f32_32x32x16_bf16 v[2:17], v[190:193], v[94:97], v[2:17]
	v_mfma_f32_32x32x16_bf16 v[50:65], v[178:181], v[98:101], v[50:65]
	ds_read_b64_tr_b16 v[114:115], v234 offset:0x4400
	ds_read_b64_tr_b16 v[116:117], v234 offset:0x4c00
	ds_read_b64_tr_b16 v[118:119], v234 offset:0x5400
	ds_read_b64_tr_b16 v[120:121], v234 offset:0x5c00
	ds_read_b64_tr_b16 v[122:123], v234 offset:0x6400
	ds_read_b64_tr_b16 v[124:125], v234 offset:0x6c00
	ds_read_b64_tr_b16 v[126:127], v234 offset:0x7400
	v_mfma_f32_32x32x16_bf16 v[50:65], v[182:185], v[102:105], v[50:65]
	ds_read_b64_tr_b16 v[128:129], v234 offset:0x7c00
	s_waitcnt lgkmcnt(0)
	v_mfma_f32_32x32x16_bf16 v[50:65], v[186:189], v[106:109], v[50:65]
	v_mfma_f32_32x32x16_bf16 v[50:65], v[190:193], v[110:113], v[50:65]
	v_mfma_f32_32x32x16_bf16 v[34:49], v[178:181], v[114:117], v[34:49]
	ds_read_b64_tr_b16 v[240:241], v234 offset:0x4600
	ds_read_b64_tr_b16 v[242:243], v234 offset:0x4e00
	ds_read_b64_tr_b16 v[244:245], v234 offset:0x5600
	ds_read_b64_tr_b16 v[246:247], v234 offset:0x5e00
	ds_read_b64_tr_b16 v[248:249], v234 offset:0x6600
	ds_read_b64_tr_b16 v[250:251], v234 offset:0x6e00
	ds_read_b64_tr_b16 v[194:195], v234 offset:0x7600
	v_mfma_f32_32x32x16_bf16 v[34:49], v[182:185], v[118:121], v[34:49]
	ds_read_b64_tr_b16 v[196:197], v234 offset:0x7e00
	s_waitcnt lgkmcnt(0)
	v_mfma_f32_32x32x16_bf16 v[34:49], v[186:189], v[122:125], v[34:49]
	v_mfma_f32_32x32x16_bf16 v[34:49], v[190:193], v[126:129], v[34:49]
	v_mfma_f32_32x32x16_bf16 v[18:33], v[178:181], v[240:243], v[18:33]
	s_mov_b64 s[40:41], 0
	v_mfma_f32_32x32x16_bf16 v[18:33], v[182:185], v[244:247], v[18:33]
	v_mfma_f32_32x32x16_bf16 v[18:33], v[186:189], v[248:251], v[18:33]
	v_mfma_f32_32x32x16_bf16 v[18:33], v[190:193], v[194:197], v[18:33]
.LBB0_828:
	s_andn2_b64 vcc, exec, s[40:41]
	s_cbranch_vccnz .LBB0_817
	ds_read_b64_tr_b16 v[66:67], v234 offset:0
	ds_read_b64_tr_b16 v[68:69], v234 offset:0x800
	ds_read_b64_tr_b16 v[70:71], v234 offset:0x1000
	ds_read_b64_tr_b16 v[72:73], v234 offset:0x1800
	ds_read_b64_tr_b16 v[74:75], v234 offset:0x2000
	ds_read_b64_tr_b16 v[76:77], v234 offset:0x2800
	ds_read_b64_tr_b16 v[78:79], v234 offset:0x3000
	ds_read_b64_tr_b16 v[80:81], v234 offset:0x3800
	s_waitcnt lgkmcnt(0)
	s_nop 0
	v_mfma_f32_32x32x16_bf16 v[2:17], v[178:181], v[66:69], v[2:17]
	ds_read_b64_tr_b16 v[66:67], v234 offset:0x200
	ds_read_b64_tr_b16 v[68:69], v234 offset:0xa00
	v_mfma_f32_32x32x16_bf16 v[2:17], v[182:185], v[70:73], v[2:17]
	ds_read_b64_tr_b16 v[70:71], v234 offset:0x1200
	ds_read_b64_tr_b16 v[72:73], v234 offset:0x1a00
	v_mfma_f32_32x32x16_bf16 v[2:17], v[186:189], v[74:77], v[2:17]
	ds_read_b64_tr_b16 v[74:75], v234 offset:0x2200
	ds_read_b64_tr_b16 v[76:77], v234 offset:0x2a00
	v_mfma_f32_32x32x16_bf16 v[2:17], v[190:193], v[78:81], v[2:17]
	ds_read_b64_tr_b16 v[78:79], v234 offset:0x3200
	ds_read_b64_tr_b16 v[80:81], v234 offset:0x3a00
	s_waitcnt lgkmcnt(0)
	v_mfma_f32_32x32x16_bf16 v[50:65], v[178:181], v[66:69], v[50:65]
	ds_read_b64_tr_b16 v[66:67], v234 offset:0x400
	ds_read_b64_tr_b16 v[68:69], v234 offset:0xc00
	v_mfma_f32_32x32x16_bf16 v[50:65], v[182:185], v[70:73], v[50:65]
	ds_read_b64_tr_b16 v[70:71], v234 offset:0x1400
	ds_read_b64_tr_b16 v[72:73], v234 offset:0x1c00
	v_mfma_f32_32x32x16_bf16 v[50:65], v[186:189], v[74:77], v[50:65]
	ds_read_b64_tr_b16 v[74:75], v234 offset:0x2400
	ds_read_b64_tr_b16 v[76:77], v234 offset:0x2c00
	v_mfma_f32_32x32x16_bf16 v[50:65], v[190:193], v[78:81], v[50:65]
	ds_read_b64_tr_b16 v[78:79], v234 offset:0x3400
	ds_read_b64_tr_b16 v[80:81], v234 offset:0x3c00
	s_waitcnt lgkmcnt(0)
	v_mfma_f32_32x32x16_bf16 v[34:49], v[178:181], v[66:69], v[34:49]
	ds_read_b64_tr_b16 v[66:67], v234 offset:0x600
	ds_read_b64_tr_b16 v[68:69], v234 offset:0xe00
	v_mfma_f32_32x32x16_bf16 v[34:49], v[182:185], v[70:73], v[34:49]
	ds_read_b64_tr_b16 v[70:71], v234 offset:0x1600
	ds_read_b64_tr_b16 v[72:73], v234 offset:0x1e00
	v_mfma_f32_32x32x16_bf16 v[34:49], v[186:189], v[74:77], v[34:49]
	ds_read_b64_tr_b16 v[74:75], v234 offset:0x2600
	ds_read_b64_tr_b16 v[76:77], v234 offset:0x2e00
	v_mfma_f32_32x32x16_bf16 v[34:49], v[190:193], v[78:81], v[34:49]
	ds_read_b64_tr_b16 v[78:79], v234 offset:0x3600
	ds_read_b64_tr_b16 v[80:81], v234 offset:0x3e00
	s_waitcnt lgkmcnt(0)
	v_mfma_f32_32x32x16_bf16 v[18:33], v[178:181], v[66:69], v[18:33]
	v_mfma_f32_32x32x16_bf16 v[18:33], v[182:185], v[70:73], v[18:33]
	v_mfma_f32_32x32x16_bf16 v[18:33], v[186:189], v[74:77], v[18:33]
	v_mfma_f32_32x32x16_bf16 v[18:33], v[190:193], v[78:81], v[18:33]
	s_branch .LBB0_817

; template <int VB>
; __device__ __forceinline__ void pv_tile(f32x16* o, int vb0, bf16x8 pa0, bf16x8 pa1, bf16x8 pa2, bf16x8 pa3) {
;     ...
;     PV_D0(0); PV_D0(1); PV_D0(2); PV_D0(3);
;     ...
; }
; template <int TYPE>
; __device__ __forceinline__ void attn_item(const Params& p, int layer, int head, int qb, int mode, LAS unsigned char* lds) {
;     ...
;             { auto rr = __builtin_amdgcn_permlane32_swap(__float_as_uint(ps), __float_as_uint(ps), false, false);
;               ps = __uint_as_float(rr[0]) + __uint_as_float(rr[1]); }
;             l_reg = l_reg * alpha + ps;
.LBB0_857:
	s_cmp_lg_u32 s11, 0
	s_mov_b64 s[4:5], -1
	s_cbranch_scc0 .LBB0_859
	ds_read_b64_tr_b16 v[82:83], v204 offset:0x4000
	ds_read_b64_tr_b16 v[84:85], v204 offset:0x4800
	ds_read_b64_tr_b16 v[86:87], v204 offset:0x5000
	ds_read_b64_tr_b16 v[88:89], v204 offset:0x5800
	ds_read_b64_tr_b16 v[90:91], v204 offset:0x6000
	ds_read_b64_tr_b16 v[92:93], v204 offset:0x6800
	ds_read_b64_tr_b16 v[94:95], v204 offset:0x7000
	ds_read_b64_tr_b16 v[96:97], v204 offset:0x7800
	s_waitcnt lgkmcnt(0)
	s_nop 0
	v_mfma_f32_32x32x16_bf16 v[50:65], v[162:165], v[82:85], v[50:65]
	ds_read_b64_tr_b16 v[98:99], v204 offset:0x4200
	ds_read_b64_tr_b16 v[100:101], v204 offset:0x4a00
	ds_read_b64_tr_b16 v[102:103], v204 offset:0x5200
	ds_read_b64_tr_b16 v[104:105], v204 offset:0x5a00
	ds_read_b64_tr_b16 v[106:107], v204 offset:0x6200
	ds_read_b64_tr_b16 v[108:109], v204 offset:0x6a00
	ds_read_b64_tr_b16 v[110:111], v204 offset:0x7200
	v_mfma_f32_32x32x16_bf16 v[50:65], v[166:169], v[86:89], v[50:65]
	ds_read_b64_tr_b16 v[112:113], v204 offset:0x7a00
	s_waitcnt lgkmcnt(0)
	v_mfma_f32_32x32x16_bf16 v[50:65], v[170:173], v[90:93], v[50:65]
	v_mfma_f32_32x32x16_bf16 v[50:65], v[174:177], v[94:97], v[50:65]
	v_mfma_f32_32x32x16_bf16 v[34:49], v[162:165], v[98:101], v[34:49]
	ds_read_b64_tr_b16 v[114:115], v204 offset:0x4400
	ds_read_b64_tr_b16 v[116:117], v204 offset:0x4c00
	ds_read_b64_tr_b16 v[118:119], v204 offset:0x5400
	ds_read_b64_tr_b16 v[120:121], v204 offset:0x5c00
	ds_read_b64_tr_b16 v[122:123], v204 offset:0x6400
	ds_read_b64_tr_b16 v[124:125], v204 offset:0x6c00
	ds_read_b64_tr_b16 v[126:127], v204 offset:0x7400
	v_mfma_f32_32x32x16_bf16 v[34:49], v[166:169], v[102:105], v[34:49]
	ds_read_b64_tr_b16 v[128:129], v204 offset:0x7c00
	s_waitcnt lgkmcnt(0)
	v_mfma_f32_32x32x16_bf16 v[34:49], v[170:173], v[106:109], v[34:49]
	v_mfma_f32_32x32x16_bf16 v[34:49], v[174:177], v[110:113], v[34:49]
	v_mfma_f32_32x32x16_bf16 v[18:33], v[162:165], v[114:117], v[18:33]
	ds_read_b64_tr_b16 v[230:231], v204 offset:0x4600
	ds_read_b64_tr_b16 v[232:233], v204 offset:0x4e00
	ds_read_b64_tr_b16 v[234:235], v204 offset:0x5600
	ds_read_b64_tr_b16 v[236:237], v204 offset:0x5e00
	ds_read_b64_tr_b16 v[238:239], v204 offset:0x6600
	ds_read_b64_tr_b16 v[240:241], v204 offset:0x6e00
	ds_read_b64_tr_b16 v[242:243], v204 offset:0x7600
	v_mfma_f32_32x32x16_bf16 v[18:33], v[166:169], v[118:121], v[18:33]
	ds_read_b64_tr_b16 v[244:245], v204 offset:0x7e00
	s_waitcnt lgkmcnt(0)
	v_mfma_f32_32x32x16_bf16 v[18:33], v[170:173], v[122:125], v[18:33]
	v_mfma_f32_32x32x16_bf16 v[18:33], v[174:177], v[126:129], v[18:33]
	v_mfma_f32_32x32x16_bf16 v[2:17], v[162:165], v[230:233], v[2:17]
	s_mov_b64 s[4:5], 0
	v_mfma_f32_32x32x16_bf16 v[2:17], v[166:169], v[234:237], v[2:17]
	v_mfma_f32_32x32x16_bf16 v[2:17], v[170:173], v[238:241], v[2:17]
	v_mfma_f32_32x32x16_bf16 v[2:17], v[174:177], v[242:245], v[2:17]
.LBB0_859:
	s_andn2_b64 vcc, exec, s[4:5]
	s_cbranch_vccnz .LBB0_861
	ds_read_b64_tr_b16 v[66:67], v204 offset:0
	ds_read_b64_tr_b16 v[68:69], v204 offset:0x800
	ds_read_b64_tr_b16 v[70:71], v204 offset:0x1000
	ds_read_b64_tr_b16 v[72:73], v204 offset:0x1800
	ds_read_b64_tr_b16 v[74:75], v204 offset:0x2000
	ds_read_b64_tr_b16 v[76:77], v204 offset:0x2800
	ds_read_b64_tr_b16 v[78:79], v204 offset:0x3000
	ds_read_b64_tr_b16 v[80:81], v204 offset:0x3800
	s_waitcnt lgkmcnt(0)
	s_nop 0
	v_mfma_f32_32x32x16_bf16 v[50:65], v[162:165], v[66:69], v[50:65]
	ds_read_b64_tr_b16 v[66:67], v204 offset:0x200
	ds_read_b64_tr_b16 v[68:69], v204 offset:0xa00
	v_mfma_f32_32x32x16_bf16 v[50:65], v[166:169], v[70:73], v[50:65]
	ds_read_b64_tr_b16 v[70:71], v204 offset:0x1200
	ds_read_b64_tr_b16 v[72:73], v204 offset:0x1a00
	v_mfma_f32_32x32x16_bf16 v[50:65], v[170:173], v[74:77], v[50:65]
	ds_read_b64_tr_b16 v[74:75], v204 offset:0x2200
	ds_read_b64_tr_b16 v[76:77], v204 offset:0x2a00
	v_mfma_f32_32x32x16_bf16 v[50:65], v[174:177], v[78:81], v[50:65]
	ds_read_b64_tr_b16 v[78:79], v204 offset:0x3200
	ds_read_b64_tr_b16 v[80:81], v204 offset:0x3a00
	s_waitcnt lgkmcnt(0)
	v_mfma_f32_32x32x16_bf16 v[34:49], v[162:165], v[66:69], v[34:49]
	ds_read_b64_tr_b16 v[66:67], v204 offset:0x400
	ds_read_b64_tr_b16 v[68:69], v204 offset:0xc00
	v_mfma_f32_32x32x16_bf16 v[34:49], v[166:169], v[70:73], v[34:49]
	ds_read_b64_tr_b16 v[70:71], v204 offset:0x1400
	ds_read_b64_tr_b16 v[72:73], v204 offset:0x1c00
	v_mfma_f32_32x32x16_bf16 v[34:49], v[170:173], v[74:77], v[34:49]
	ds_read_b64_tr_b16 v[74:75], v204 offset:0x2400
	ds_read_b64_tr_b16 v[76:77], v204 offset:0x2c00
	v_mfma_f32_32x32x16_bf16 v[34:49], v[174:177], v[78:81], v[34:49]
	ds_read_b64_tr_b16 v[78:79], v204 offset:0x3400
	ds_read_b64_tr_b16 v[80:81], v204 offset:0x3c00
	s_waitcnt lgkmcnt(0)
	v_mfma_f32_32x32x16_bf16 v[18:33], v[162:165], v[66:69], v[18:33]
	ds_read_b64_tr_b16 v[66:67], v204 offset:0x600
	ds_read_b64_tr_b16 v[68:69], v204 offset:0xe00
	v_mfma_f32_32x32x16_bf16 v[18:33], v[166:169], v[70:73], v[18:33]
	ds_read_b64_tr_b16 v[70:71], v204 offset:0x1600
	ds_read_b64_tr_b16 v[72:73], v204 offset:0x1e00
	v_mfma_f32_32x32x16_bf16 v[18:33], v[170:173], v[74:77], v[18:33]
	ds_read_b64_tr_b16 v[74:75], v204 offset:0x2600
	ds_read_b64_tr_b16 v[76:77], v204 offset:0x2e00
	v_mfma_f32_32x32x16_bf16 v[18:33], v[174:177], v[78:81], v[18:33]
	ds_read_b64_tr_b16 v[78:79], v204 offset:0x3600
	ds_read_b64_tr_b16 v[80:81], v204 offset:0x3e00
	s_waitcnt lgkmcnt(0)
	v_mfma_f32_32x32x16_bf16 v[2:17], v[162:165], v[66:69], v[2:17]
	v_mfma_f32_32x32x16_bf16 v[2:17], v[166:169], v[70:73], v[2:17]
	v_mfma_f32_32x32x16_bf16 v[2:17], v[170:173], v[74:77], v[2:17]
	v_mfma_f32_32x32x16_bf16 v[2:17], v[174:177], v[78:81], v[2:17]
.LBB0_861:
	s_nop 0
	v_add_f32_e32 v66, v228, v229
	v_fmac_f32_e32 v66, v226, v0
	v_mov_b32_e32 v226, v66
